# attention loop: exps between the 1st and 2nd QK^T MFMA moved ahead of the first MFMA's K-fragment wait
# speedup vs baseline: 1.0193x; 1.0006x over previous
.LBB0_433:
	ds_read_b128 v[64:67], v166 offset:49152
	ds_read_b128 v[68:71], v166 offset:57344
	ds_read_b128 v[176:179], v167 offset:49152
	ds_read_b128 v[198:201], v167 offset:57344
	ds_read_b128 v[202:205], v168 offset:49152
	ds_read_b128 v[210:213], v168 offset:57344
	s_add_u32 m0, s86, 0x8000
	s_nop 0
	global_load_lds_dwordx4 v247, s[82:83]
	s_add_u32 m0, s86, 0x8400
	s_nop 0
	global_load_lds_dwordx4 v248, s[82:83]
	s_add_u32 s82, s82, 0x8000
	s_addc_u32 s83, s83, 0
	v_exp_f32_e32 v142, v142
	v_exp_f32_e32 v143, v143
	v_exp_f32_e32 v180, v140
	v_exp_f32_e32 v181, v141
	v_exp_f32_e32 v206, v138
	v_exp_f32_e32 v207, v135
	v_exp_f32_e32 v148, v148
	v_exp_f32_e32 v149, v149
	v_exp_f32_e32 v209, v146
	s_waitcnt lgkmcnt(5)
	v_mfma_f32_32x32x16_bf16 v[80:95], v[64:67], v[124:127], 0
	s_waitcnt lgkmcnt(4)
	v_mfma_f32_32x32x16_bf16 v[64:79], v[68:71], v[124:127], 0
	v_cvt_pk_bf16_f32 v135, v192, v193
	v_cvt_pk_bf16_f32 v138, v182, v183
	v_cvt_pk_bf16_f32 v140, v185, v187
	v_cvt_pk_bf16_f32 v141, v188, v189
	s_nop 0
	s_waitcnt lgkmcnt(3)
	v_mfma_f32_32x32x16_bf16 v[80:95], v[176:179], v[120:123], v[80:95]
	ds_read_b128 v[176:179], v169 offset:49152
	ds_read_b128 v[214:217], v169 offset:57344
	ds_read_b128 v[218:221], v170 offset:49152
	ds_read_b128 v[222:225], v170 offset:57344
	ds_read_b128 v[226:229], v171 offset:49152
	ds_read_b128 v[230:233], v171 offset:57344
	ds_read_b128 v[234:237], v172 offset:49152
	ds_read_b128 v[238:241], v172 offset:57344
	s_waitcnt lgkmcnt(10)
	v_mfma_f32_32x32x16_bf16 v[64:79], v[198:201], v[120:123], v[64:79]
	ds_read_b128 v[198:201], v173 offset:49152
	ds_read_b128 v[242:245], v173 offset:57344
	s_waitcnt lgkmcnt(11)
	v_mfma_f32_32x32x16_bf16 v[80:95], v[202:205], v[112:115], v[80:95]
	v_exp_f32_e32 v205, v134
	v_add_f32_e32 v134, v191, v190
	v_add_f32_e32 v134, v192, v134
	v_add_f32_e32 v134, v193, v134
	v_add_f32_e32 v134, v194, v134
	v_add_f32_e32 v134, v196, v134
	s_waitcnt lgkmcnt(10)
	v_mfma_f32_32x32x16_bf16 v[64:79], v[210:213], v[112:115], v[64:79]
	v_add_f32_e32 v134, v195, v134
	v_add_f32_e32 v134, v197, v134
	v_add_f32_e32 v134, v182, v134
	v_add_f32_e32 v134, v183, v134
	v_add_f32_e32 v134, v184, v134
	v_add_f32_e32 v134, v186, v134
	v_add_f32_e32 v134, v185, v134
	s_waitcnt lgkmcnt(9)
	v_mfma_f32_32x32x16_bf16 v[80:95], v[176:179], v[116:119], v[80:95]
	v_add_f32_e32 v134, v187, v134
	v_add_f32_e32 v134, v188, v134
	v_add_f32_e32 v134, v189, v134
	v_add_f32_e32 v134, v142, v134
	v_exp_f32_e32 v202, v139
	v_add_f32_e32 v134, v143, v134
	v_exp_f32_e32 v203, v136
	s_waitcnt lgkmcnt(8)
	v_mfma_f32_32x32x16_bf16 v[64:79], v[214:217], v[116:119], v[64:79]
	v_add_f32_e32 v134, v180, v134
	v_exp_f32_e32 v204, v137
	v_add_f32_e32 v134, v181, v134
	v_add_f32_e32 v134, v206, v134
	v_add_f32_e32 v134, v202, v134
	v_add_f32_e32 v134, v203, v134
	v_add_f32_e32 v134, v204, v134
	s_waitcnt lgkmcnt(7)
	v_mfma_f32_32x32x16_bf16 v[80:95], v[218:221], v[108:111], v[80:95]
	v_add_f32_e32 v134, v205, v134
	v_exp_f32_e32 v210, v147
	v_add_f32_e32 v134, v207, v134
	v_exp_f32_e32 v211, v144
	v_add_f32_e32 v134, v148, v134
	v_exp_f32_e32 v212, v145
	v_add_f32_e32 v134, v149, v134
	s_waitcnt lgkmcnt(6)
	v_mfma_f32_32x32x16_bf16 v[64:79], v[222:225], v[108:111], v[64:79]
	v_add_f32_e32 v134, v209, v134
	v_add_f32_e32 v134, v210, v134
	v_add_f32_e32 v134, v211, v134
	v_add_f32_e32 v176, v212, v134
	v_cvt_pk_bf16_f32 v134, v190, v191
	v_cvt_pk_bf16_f32 v136, v194, v196
	s_waitcnt lgkmcnt(5)
	v_mfma_f32_32x32x16_bf16 v[80:95], v[226:229], v[104:107], v[80:95]
	v_cvt_pk_bf16_f32 v137, v195, v197
	v_cvt_pk_bf16_f32 v139, v184, v186
	v_cvt_pk_bf16_f32 v142, v142, v143
	s_waitcnt lgkmcnt(4)
	v_mfma_f32_32x32x16_bf16 v[64:79], v[230:233], v[104:107], v[64:79]
	ds_read_b64_tr_b16 v[218:219], v161 offset:0
	ds_read_b64_tr_b16 v[220:221], v161 offset:2048
	ds_read_b64_tr_b16 v[222:223], v161 offset:4096
	ds_read_b64_tr_b16 v[224:225], v161 offset:6144
	ds_read_b64_tr_b16 v[226:227], v161 offset:8192
	ds_read_b64_tr_b16 v[228:229], v161 offset:10240
	ds_read_b64_tr_b16 v[230:231], v161 offset:12288
	ds_read_b64_tr_b16 v[232:233], v161 offset:14336
	v_cvt_pk_bf16_f32 v143, v180, v181
	v_cvt_pk_bf16_f32 v144, v206, v202
	v_cvt_pk_bf16_f32 v145, v203, v204
	v_cvt_pk_bf16_f32 v146, v205, v207
	v_cvt_pk_bf16_f32 v147, v148, v149
	v_cvt_pk_bf16_f32 v148, v209, v210
	v_cvt_pk_bf16_f32 v149, v211, v212
	s_waitcnt lgkmcnt(11)
	v_mfma_f32_32x32x16_bf16 v[80:95], v[234:237], v[100:103], v[80:95]
	s_waitcnt lgkmcnt(10)
	v_mfma_f32_32x32x16_bf16 v[64:79], v[238:241], v[100:103], v[64:79]
	s_waitcnt lgkmcnt(9)
	v_mfma_f32_32x32x16_bf16 v[80:95], v[198:201], v[96:99], v[80:95]
	s_waitcnt lgkmcnt(8)
	v_mfma_f32_32x32x16_bf16 v[64:79], v[242:245], v[96:99], v[64:79]
	s_waitcnt lgkmcnt(0)
	s_nop 0
	v_mfma_f32_32x32x16_bf16 v[0:15], v[134:137], v[218:221], v[0:15]
	ds_read_b64_tr_b16 v[196:197], v161 offset:0x200
	ds_read_b64_tr_b16 v[198:199], v161 offset:0xa00
	v_max_f32_e32 v234, v80, v81
	v_max3_f32 v234, v234, v82, v83
	v_max3_f32 v234, v234, v84, v85
	v_max3_f32 v234, v234, v86, v87
	v_max3_f32 v234, v234, v88, v89
	v_mfma_f32_32x32x16_bf16 v[0:15], v[138:141], v[222:225], v[0:15]
	ds_read_b64_tr_b16 v[200:201], v161 offset:0x1200
	ds_read_b64_tr_b16 v[202:203], v161 offset:0x1a00
	v_max3_f32 v234, v234, v90, v91
	v_max3_f32 v234, v234, v92, v93
	v_max3_f32 v234, v234, v94, v95
	v_max3_f32 v234, v234, v64, v65
	v_max3_f32 v234, v234, v66, v67
	v_mfma_f32_32x32x16_bf16 v[0:15], v[142:145], v[226:229], v[0:15]
	ds_read_b64_tr_b16 v[204:205], v161 offset:0x2200
	ds_read_b64_tr_b16 v[206:207], v161 offset:0x2a00
	ds_read_b64_tr_b16 v[214:215], v161 offset:0x3200
	ds_read_b64_tr_b16 v[216:217], v161 offset:0x3a00
	v_max3_f32 v234, v234, v68, v69
	v_max3_f32 v234, v234, v70, v71
	v_max3_f32 v234, v234, v72, v73
	v_max3_f32 v234, v234, v74, v75
	v_max3_f32 v234, v234, v76, v77
	s_waitcnt lgkmcnt(0)
	v_mfma_f32_32x32x16_bf16 v[0:15], v[146:149], v[230:233], v[0:15]
	v_max3_f32 v234, v234, v78, v79
	v_mov_b32_e32 v235, v234
	v_mfma_f32_32x32x16_bf16 v[48:63], v[134:137], v[196:199], v[48:63]
	ds_read_b64_tr_b16 v[196:197], v161 offset:0x400
	ds_read_b64_tr_b16 v[198:199], v161 offset:0xc00
	v_permlane32_swap_b32_e32 v234, v235
	v_max_f32_e32 v234, v234, v235
	v_mfma_f32_32x32x16_bf16 v[48:63], v[138:141], v[200:203], v[48:63]
	ds_read_b64_tr_b16 v[200:201], v161 offset:0x1400
	ds_read_b64_tr_b16 v[202:203], v161 offset:0x1c00
	v_sub_f32_e32 v235, v234, v175
	v_max_f32_e32 v234, v175, v234
	v_sub_f32_e32 v236, v175, v234
	v_mul_f32_e32 v236, 0x3e0293ee, v236
	v_mfma_f32_32x32x16_bf16 v[48:63], v[142:145], v[204:207], v[48:63]
	ds_read_b64_tr_b16 v[204:205], v161 offset:0x2400
	ds_read_b64_tr_b16 v[206:207], v161 offset:0x2c00
	ds_read_b64_tr_b16 v[210:211], v161 offset:0x3400
	ds_read_b64_tr_b16 v[212:213], v161 offset:0x3c00
	v_exp_f32_e32 v236, v236
	v_cmp_ge_f32_e32 vcc, s15, v235
	s_cmp_eq_u64 vcc, exec
	s_cselect_b64 s[8:9], -1, 0
	s_waitcnt lgkmcnt(0)
	v_mfma_f32_32x32x16_bf16 v[48:63], v[146:149], v[214:217], v[48:63]
	v_cndmask_b32_e64 v179, v236, 1.0, s[8:9]
	v_cndmask_b32_e64 v234, v234, v175, s[8:9]
	v_mul_f32_e32 v238, 0xbe0293ee, v234
	v_fmamk_f32 v88, v88, 0x3e0293ee, v238
	v_fmamk_f32 v89, v89, 0x3e0293ee, v238
	v_fmamk_f32 v80, v80, 0x3e0293ee, v238
	v_fmamk_f32 v81, v81, 0x3e0293ee, v238
	v_mfma_f32_32x32x16_bf16 v[32:47], v[134:137], v[196:199], v[32:47]
	ds_read_b64_tr_b16 v[196:197], v161 offset:0x600
	ds_read_b64_tr_b16 v[198:199], v161 offset:0xe00
	v_fmamk_f32 v82, v82, 0x3e0293ee, v238
	v_fmamk_f32 v83, v83, 0x3e0293ee, v238
	v_fmamk_f32 v84, v84, 0x3e0293ee, v238
	v_fmamk_f32 v85, v85, 0x3e0293ee, v238
	v_fmamk_f32 v86, v86, 0x3e0293ee, v238
	v_fmamk_f32 v87, v87, 0x3e0293ee, v238
	v_fmamk_f32 v90, v90, 0x3e0293ee, v238
	v_fmamk_f32 v91, v91, 0x3e0293ee, v238
	v_mfma_f32_32x32x16_bf16 v[32:47], v[138:141], v[200:203], v[32:47]
	ds_read_b64_tr_b16 v[200:201], v161 offset:0x1600
	ds_read_b64_tr_b16 v[202:203], v161 offset:0x1e00
	v_fmamk_f32 v92, v92, 0x3e0293ee, v238
	v_fmamk_f32 v93, v93, 0x3e0293ee, v238
	v_fmamk_f32 v94, v94, 0x3e0293ee, v238
	v_fmamk_f32 v95, v95, 0x3e0293ee, v238
	v_fmamk_f32 v188, v64, 0x3e0293ee, v238
	v_fmamk_f32 v189, v65, 0x3e0293ee, v238
	v_fmamk_f32 v190, v66, 0x3e0293ee, v238
	v_fmamk_f32 v191, v67, 0x3e0293ee, v238
	v_mfma_f32_32x32x16_bf16 v[32:47], v[142:145], v[204:207], v[32:47]
	ds_read_b64_tr_b16 v[204:205], v161 offset:0x2600
	ds_read_b64_tr_b16 v[206:207], v161 offset:0x2e00
	ds_read_b64_tr_b16 v[214:215], v161 offset:0x3600
	ds_read_b64_tr_b16 v[216:217], v161 offset:0x3e00
	v_fmamk_f32 v182, v70, 0x3e0293ee, v238
	v_fmamk_f32 v183, v71, 0x3e0293ee, v238
	v_fmamk_f32 v184, v72, 0x3e0293ee, v238
	v_fmamk_f32 v185, v73, 0x3e0293ee, v238
	v_fmamk_f32 v186, v74, 0x3e0293ee, v238
	v_fmamk_f32 v187, v75, 0x3e0293ee, v238
	s_waitcnt lgkmcnt(0)
	v_mfma_f32_32x32x16_bf16 v[32:47], v[146:149], v[210:213], v[32:47]
	v_fmamk_f32 v192, v68, 0x3e0293ee, v238
	v_fmamk_f32 v181, v69, 0x3e0293ee, v238
	v_fmamk_f32 v180, v76, 0x3e0293ee, v238
	v_mfma_f32_32x32x16_bf16 v[16:31], v[134:137], v[196:199], v[16:31]
	v_fmamk_f32 v193, v77, 0x3e0293ee, v238
	v_fmamk_f32 v194, v78, 0x3e0293ee, v238
	v_fmamk_f32 v177, v79, 0x3e0293ee, v238
	v_mov_b32_e32 v134, v234
	v_exp_f32_e32 v135, v88
	v_exp_f32_e32 v136, v89
	v_exp_f32_e32 v137, v90
	v_mfma_f32_32x32x16_bf16 v[16:31], v[138:141], v[200:203], v[16:31]
	v_exp_f32_e32 v139, v91
	v_exp_f32_e32 v138, v92
	v_exp_f32_e32 v140, v93
	v_exp_f32_e32 v141, v94
	v_mfma_f32_32x32x16_bf16 v[16:31], v[142:145], v[204:207], v[16:31]
	v_exp_f32_e32 v142, v95
	v_exp_f32_e32 v143, v80
	v_exp_f32_e32 v144, v81
	v_exp_f32_e32 v145, v82
	v_mfma_f32_32x32x16_bf16 v[16:31], v[146:149], v[214:217], v[16:31]
	v_exp_f32_e32 v146, v83
	v_exp_f32_e32 v147, v84
	v_exp_f32_e32 v149, v85
	v_exp_f32_e32 v148, v86
	v_exp_f32_e32 v175, v87
	v_cmp_gt_f32_e32 vcc, 1.0, v179
	s_waitcnt vmcnt(0)
	s_barrier
	s_cbranch_vccz .LBB0_437
	s_and_saveexec_b64 s[2:3], s[6:7]
	ds_write_b32 v158, v179 offset:128
	s_or_b64 exec, exec, s[2:3]
	s_waitcnt lgkmcnt(0)
	v_add_u32_e32 v234, v131, v128
	ds_read_b128 v[218:221], v234 offset:224
	ds_read_b128 v[222:225], v234 offset:192
	ds_read_b128 v[226:229], v234 offset:160
	ds_read_b128 v[230:233], v234 offset:128
	s_waitcnt lgkmcnt(3)
	v_pk_mul_f32 v[12:13], v[12:13], v[218:219]
	s_waitcnt lgkmcnt(2)
	v_pk_mul_f32 v[8:9], v[8:9], v[222:223]
	s_waitcnt lgkmcnt(1)
	v_pk_mul_f32 v[4:5], v[4:5], v[226:227]
	v_pk_mul_f32 v[14:15], v[14:15], v[220:221]
	v_pk_mul_f32 v[10:11], v[10:11], v[224:225]
	v_pk_mul_f32 v[6:7], v[6:7], v[228:229]
	s_waitcnt lgkmcnt(0)
	v_pk_mul_f32 v[2:3], v[2:3], v[232:233]
	v_pk_mul_f32 v[0:1], v[0:1], v[230:231]
	v_pk_mul_f32 v[60:61], v[60:61], v[218:219]
	v_pk_mul_f32 v[56:57], v[56:57], v[222:223]
	v_pk_mul_f32 v[52:53], v[52:53], v[226:227]
	v_pk_mul_f32 v[62:63], v[62:63], v[220:221]
	v_pk_mul_f32 v[58:59], v[58:59], v[224:225]
	v_pk_mul_f32 v[54:55], v[54:55], v[228:229]
	v_pk_mul_f32 v[50:51], v[50:51], v[232:233]
	v_pk_mul_f32 v[48:49], v[48:49], v[230:231]
	v_pk_mul_f32 v[44:45], v[44:45], v[218:219]
	v_pk_mul_f32 v[40:41], v[40:41], v[222:223]
	v_pk_mul_f32 v[36:37], v[36:37], v[226:227]
	v_pk_mul_f32 v[46:47], v[46:47], v[220:221]
	v_pk_mul_f32 v[42:43], v[42:43], v[224:225]
	v_pk_mul_f32 v[38:39], v[38:39], v[228:229]
	v_pk_mul_f32 v[34:35], v[34:35], v[232:233]
	v_pk_mul_f32 v[32:33], v[32:33], v[230:231]
	v_pk_mul_f32 v[28:29], v[28:29], v[218:219]
	v_pk_mul_f32 v[24:25], v[24:25], v[222:223]
	v_pk_mul_f32 v[20:21], v[20:21], v[226:227]
	v_pk_mul_f32 v[30:31], v[30:31], v[220:221]
	v_pk_mul_f32 v[26:27], v[26:27], v[224:225]
	v_pk_mul_f32 v[22:23], v[22:23], v[228:229]
	v_pk_mul_f32 v[18:19], v[18:19], v[232:233]
	v_pk_mul_f32 v[16:17], v[16:17], v[230:231]
.LBB0_437:
	ds_read_b128 v[64:67], v166 offset:32768
	ds_read_b128 v[68:71], v166 offset:40960
	ds_read_b128 v[196:199], v167 offset:32768
	ds_read_b128 v[200:203], v167 offset:40960
	ds_read_b128 v[204:207], v168 offset:32768
	ds_read_b128 v[210:213], v168 offset:40960
	s_add_u32 m0, s86, 0x0
	s_nop 0
	global_load_lds_dwordx4 v249, s[84:85]
	s_add_u32 m0, s86, 0x380
	s_nop 0
	global_load_lds_dwordx4 v249, s[84:85] offset:128
	s_add_u32 s84, s84, 0x8000
	s_addc_u32 s85, s85, 0
	s_add_u32 m0, s86, 0xc000
	s_nop 0
	global_load_lds_dwordx4 v247, s[82:83]
	s_add_u32 m0, s86, 0xc400
	s_nop 0
	global_load_lds_dwordx4 v248, s[82:83]
	s_add_u32 s82, s82, 0x8000
	s_addc_u32 s83, s83, 0
	v_exp_f32_e32 v188, v188
	v_exp_f32_e32 v189, v189
	v_exp_f32_e32 v190, v190
	v_exp_f32_e32 v191, v191
	v_exp_f32_e32 v192, v192
	v_exp_f32_e32 v195, v181
	v_exp_f32_e32 v182, v182
	v_exp_f32_e32 v183, v183
	v_exp_f32_e32 v184, v184
	s_waitcnt lgkmcnt(5)
	v_mfma_f32_32x32x16_bf16 v[80:95], v[64:67], v[124:127], 0
	s_waitcnt lgkmcnt(4)
	v_mfma_f32_32x32x16_bf16 v[64:79], v[68:71], v[124:127], 0
	v_exp_f32_e32 v185, v185
	v_exp_f32_e32 v186, v186
	v_exp_f32_e32 v187, v187
	v_exp_f32_e32 v193, v193
	v_exp_f32_e32 v194, v194
	v_exp_f32_e32 v177, v177
	s_waitcnt lgkmcnt(3)
	v_mfma_f32_32x32x16_bf16 v[80:95], v[196:199], v[120:123], v[80:95]
	ds_read_b128 v[196:199], v169 offset:32768
	ds_read_b128 v[214:217], v169 offset:40960
	ds_read_b128 v[218:221], v170 offset:32768
	ds_read_b128 v[222:225], v170 offset:40960
	ds_read_b128 v[226:229], v171 offset:32768
	ds_read_b128 v[230:233], v171 offset:40960
	ds_read_b128 v[234:237], v172 offset:32768
	ds_read_b128 v[238:241], v172 offset:40960
	s_waitcnt lgkmcnt(10)
	v_mfma_f32_32x32x16_bf16 v[64:79], v[200:203], v[120:123], v[64:79]
	ds_read_b128 v[200:203], v173 offset:32768
	ds_read_b128 v[242:245], v173 offset:40960
	s_waitcnt lgkmcnt(11)
	v_mfma_f32_32x32x16_bf16 v[80:95], v[204:207], v[112:115], v[80:95]
	v_exp_f32_e32 v204, v180
	v_add_f32_e32 v180, v144, v143
	v_add_f32_e32 v180, v145, v180
	v_add_f32_e32 v180, v146, v180
	v_add_f32_e32 v180, v147, v180
	v_add_f32_e32 v180, v149, v180
	s_waitcnt lgkmcnt(10)
	v_mfma_f32_32x32x16_bf16 v[64:79], v[210:213], v[112:115], v[64:79]
	v_add_f32_e32 v180, v148, v180
	v_add_f32_e32 v180, v175, v180
	v_add_f32_e32 v180, v135, v180
	v_add_f32_e32 v180, v136, v180
	v_add_f32_e32 v180, v137, v180
	v_add_f32_e32 v180, v139, v180
	v_add_f32_e32 v180, v138, v180
	s_waitcnt lgkmcnt(9)
	v_mfma_f32_32x32x16_bf16 v[80:95], v[196:199], v[116:119], v[80:95]
	v_add_f32_e32 v180, v140, v180
	v_add_f32_e32 v180, v141, v180
	v_add_f32_e32 v180, v142, v180
	v_add_f32_e32 v180, v188, v180
	v_add_f32_e32 v180, v189, v180
	v_add_f32_e32 v180, v190, v180
	v_add_f32_e32 v180, v191, v180
	s_waitcnt lgkmcnt(8)
	v_mfma_f32_32x32x16_bf16 v[64:79], v[214:217], v[116:119], v[64:79]
	v_add_f32_e32 v180, v192, v180
	v_add_f32_e32 v180, v195, v180
	v_add_f32_e32 v180, v182, v180
	v_add_f32_e32 v180, v183, v180
	v_add_f32_e32 v180, v184, v180
	v_add_f32_e32 v180, v185, v180
	v_add_f32_e32 v180, v186, v180
	s_waitcnt lgkmcnt(7)
	v_mfma_f32_32x32x16_bf16 v[80:95], v[218:221], v[108:111], v[80:95]
	v_add_f32_e32 v180, v187, v180
	v_add_f32_e32 v180, v204, v180
	v_add_f32_e32 v180, v193, v180
	v_add_f32_e32 v180, v194, v180
	v_add_f32_e32 v180, v177, v180
	s_waitcnt lgkmcnt(6)
	v_mfma_f32_32x32x16_bf16 v[64:79], v[222:225], v[108:111], v[64:79]
	v_cvt_pk_bf16_f32 v144, v143, v144
	v_cvt_pk_bf16_f32 v145, v145, v146
	v_cvt_pk_bf16_f32 v146, v147, v149
	v_cvt_pk_bf16_f32 v147, v148, v175
	v_cvt_pk_bf16_f32 v136, v135, v136
	v_cvt_pk_bf16_f32 v137, v137, v139
	v_cvt_pk_bf16_f32 v138, v138, v140
	s_waitcnt lgkmcnt(5)
	v_mfma_f32_32x32x16_bf16 v[80:95], v[226:229], v[104:107], v[80:95]
	v_cvt_pk_bf16_f32 v139, v141, v142
	v_cvt_pk_bf16_f32 v140, v188, v189
	v_cvt_pk_bf16_f32 v141, v190, v191
	v_cvt_pk_bf16_f32 v142, v192, v195
	v_cvt_pk_bf16_f32 v143, v182, v183
	v_cvt_pk_bf16_f32 v182, v184, v185
	v_cvt_pk_bf16_f32 v183, v186, v187
	s_waitcnt lgkmcnt(4)
	v_mfma_f32_32x32x16_bf16 v[64:79], v[230:233], v[104:107], v[64:79]
	ds_read_b64_tr_b16 v[218:219], v160 offset:0
	ds_read_b64_tr_b16 v[220:221], v160 offset:2048
	ds_read_b64_tr_b16 v[222:223], v160 offset:4096
	ds_read_b64_tr_b16 v[224:225], v160 offset:6144
	ds_read_b64_tr_b16 v[226:227], v160 offset:8192
	ds_read_b64_tr_b16 v[228:229], v160 offset:10240
	ds_read_b64_tr_b16 v[230:231], v160 offset:12288
	ds_read_b64_tr_b16 v[232:233], v160 offset:14336
	v_cvt_pk_bf16_f32 v184, v204, v193
	v_cvt_pk_bf16_f32 v185, v194, v177
	s_waitcnt lgkmcnt(11)
	v_mfma_f32_32x32x16_bf16 v[80:95], v[234:237], v[100:103], v[80:95]
	s_waitcnt lgkmcnt(10)
	v_mfma_f32_32x32x16_bf16 v[64:79], v[238:241], v[100:103], v[64:79]
	s_waitcnt lgkmcnt(9)
	v_mfma_f32_32x32x16_bf16 v[80:95], v[200:203], v[96:99], v[80:95]
	s_waitcnt lgkmcnt(8)
	v_mfma_f32_32x32x16_bf16 v[64:79], v[242:245], v[96:99], v[64:79]
	s_waitcnt lgkmcnt(0)
	s_nop 0
	v_mfma_f32_32x32x16_bf16 v[0:15], v[144:147], v[218:221], v[0:15]
	ds_read_b64_tr_b16 v[202:203], v160 offset:0x200
	ds_read_b64_tr_b16 v[204:205], v160 offset:0xa00
	v_max_f32_e32 v242, v80, v81
	v_max3_f32 v242, v242, v82, v83
	v_max3_f32 v242, v242, v84, v85
	v_max3_f32 v242, v242, v86, v87
	v_max3_f32 v242, v242, v88, v89
	v_mfma_f32_32x32x16_bf16 v[0:15], v[136:139], v[222:225], v[0:15]
	ds_read_b64_tr_b16 v[210:211], v160 offset:0x1200
	ds_read_b64_tr_b16 v[212:213], v160 offset:0x1a00
	v_max3_f32 v242, v242, v90, v91
	v_max3_f32 v242, v242, v92, v93
	v_max3_f32 v242, v242, v94, v95
	v_max3_f32 v242, v242, v64, v65
	v_max3_f32 v242, v242, v66, v67
	v_mfma_f32_32x32x16_bf16 v[0:15], v[140:143], v[226:229], v[0:15]
	ds_read_b64_tr_b16 v[214:215], v160 offset:0x2200
	ds_read_b64_tr_b16 v[216:217], v160 offset:0x2a00
	ds_read_b64_tr_b16 v[222:223], v160 offset:0x3200
	ds_read_b64_tr_b16 v[224:225], v160 offset:0x3a00
	v_max3_f32 v242, v242, v68, v69
	v_max3_f32 v242, v242, v70, v71
	v_max3_f32 v242, v242, v72, v73
	v_max3_f32 v242, v242, v74, v75
	v_max3_f32 v242, v242, v76, v77
	s_waitcnt lgkmcnt(0)
	v_mfma_f32_32x32x16_bf16 v[0:15], v[182:185], v[230:233], v[0:15]
	v_max3_f32 v242, v242, v78, v79
	v_mov_b32_e32 v243, v242
	v_mfma_f32_32x32x16_bf16 v[48:63], v[144:147], v[202:205], v[48:63]
	ds_read_b64_tr_b16 v[202:203], v160 offset:0x400
	ds_read_b64_tr_b16 v[204:205], v160 offset:0xc00
	v_permlane32_swap_b32_e32 v242, v243
	v_max_f32_e32 v242, v242, v243
	v_mfma_f32_32x32x16_bf16 v[48:63], v[136:139], v[210:213], v[48:63]
	ds_read_b64_tr_b16 v[210:211], v160 offset:0x1400
	ds_read_b64_tr_b16 v[212:213], v160 offset:0x1c00
	v_sub_f32_e32 v243, v242, v134
	v_max_f32_e32 v242, v134, v242
	v_sub_f32_e32 v148, v134, v242
	v_mul_f32_e32 v148, 0x3e0293ee, v148
	v_mfma_f32_32x32x16_bf16 v[48:63], v[140:143], v[214:217], v[48:63]
	ds_read_b64_tr_b16 v[214:215], v160 offset:0x2400
	ds_read_b64_tr_b16 v[216:217], v160 offset:0x2c00
	ds_read_b64_tr_b16 v[218:219], v160 offset:0x3400
	ds_read_b64_tr_b16 v[220:221], v160 offset:0x3c00
	v_exp_f32_e32 v148, v148
	v_cmp_ge_f32_e32 vcc, s15, v243
	s_cmp_eq_u64 vcc, exec
	s_cselect_b64 s[8:9], -1, 0
	s_waitcnt lgkmcnt(0)
	v_mfma_f32_32x32x16_bf16 v[48:63], v[182:185], v[222:225], v[48:63]
	v_cndmask_b32_e64 v177, v148, 1.0, s[8:9]
	v_cndmask_b32_e64 v175, v242, v134, s[8:9]
	v_mul_f32_e32 v244, 0xbe0293ee, v175
	v_fmamk_f32 v80, v80, 0x3e0293ee, v244
	v_fmamk_f32 v81, v81, 0x3e0293ee, v244
	v_fmamk_f32 v82, v82, 0x3e0293ee, v244
	v_fmamk_f32 v83, v83, 0x3e0293ee, v244
	v_mfma_f32_32x32x16_bf16 v[32:47], v[144:147], v[202:205], v[32:47]
	ds_read_b64_tr_b16 v[202:203], v160 offset:0x600
	ds_read_b64_tr_b16 v[204:205], v160 offset:0xe00
	v_fmamk_f32 v84, v84, 0x3e0293ee, v244
	v_fmamk_f32 v85, v85, 0x3e0293ee, v244
	v_fmamk_f32 v86, v86, 0x3e0293ee, v244
	v_fmamk_f32 v87, v87, 0x3e0293ee, v244
	v_fmamk_f32 v88, v88, 0x3e0293ee, v244
	v_fmamk_f32 v89, v89, 0x3e0293ee, v244
	v_fmamk_f32 v90, v90, 0x3e0293ee, v244
	v_fmamk_f32 v91, v91, 0x3e0293ee, v244
	v_mfma_f32_32x32x16_bf16 v[32:47], v[136:139], v[210:213], v[32:47]
	ds_read_b64_tr_b16 v[210:211], v160 offset:0x1600
	ds_read_b64_tr_b16 v[212:213], v160 offset:0x1e00
	v_fmamk_f32 v92, v92, 0x3e0293ee, v244
	v_fmamk_f32 v93, v93, 0x3e0293ee, v244
	v_fmamk_f32 v94, v94, 0x3e0293ee, v244
	v_fmamk_f32 v95, v95, 0x3e0293ee, v244
	v_fmamk_f32 v134, v72, 0x3e0293ee, v244
	v_fmamk_f32 v135, v73, 0x3e0293ee, v244
	v_fmamk_f32 v148, v74, 0x3e0293ee, v244
	v_fmamk_f32 v149, v75, 0x3e0293ee, v244
	v_mfma_f32_32x32x16_bf16 v[32:47], v[140:143], v[214:217], v[32:47]
	ds_read_b64_tr_b16 v[214:215], v160 offset:0x2600
	ds_read_b64_tr_b16 v[216:217], v160 offset:0x2e00
	ds_read_b64_tr_b16 v[222:223], v160 offset:0x3600
	ds_read_b64_tr_b16 v[224:225], v160 offset:0x3e00
	v_exp_f32_e32 v190, v80
	v_exp_f32_e32 v191, v81
	v_exp_f32_e32 v192, v82
	s_waitcnt lgkmcnt(0)
	v_mfma_f32_32x32x16_bf16 v[32:47], v[182:185], v[218:221], v[32:47]
	v_exp_f32_e32 v193, v83
	v_exp_f32_e32 v194, v84
	v_exp_f32_e32 v196, v85
	v_mfma_f32_32x32x16_bf16 v[16:31], v[144:147], v[202:205], v[16:31]
	v_fmamk_f32 v144, v78, 0x3e0293ee, v244
	v_fmamk_f32 v145, v79, 0x3e0293ee, v244
	v_fmamk_f32 v146, v76, 0x3e0293ee, v244
	v_fmamk_f32 v147, v77, 0x3e0293ee, v244
	v_exp_f32_e32 v195, v86
	v_exp_f32_e32 v197, v87
	v_mfma_f32_32x32x16_bf16 v[16:31], v[136:139], v[210:213], v[16:31]
	v_fmamk_f32 v136, v70, 0x3e0293ee, v244
	v_fmamk_f32 v137, v71, 0x3e0293ee, v244
	v_fmamk_f32 v138, v68, 0x3e0293ee, v244
	v_fmamk_f32 v139, v69, 0x3e0293ee, v244
	v_exp_f32_e32 v186, v91
	v_exp_f32_e32 v187, v93
	v_mfma_f32_32x32x16_bf16 v[16:31], v[140:143], v[214:217], v[16:31]
	v_fmamk_f32 v140, v66, 0x3e0293ee, v244
	v_fmamk_f32 v141, v67, 0x3e0293ee, v244
	v_fmamk_f32 v142, v64, 0x3e0293ee, v244
	v_fmamk_f32 v143, v65, 0x3e0293ee, v244
	v_exp_f32_e32 v188, v94
	v_exp_f32_e32 v189, v95
	v_mfma_f32_32x32x16_bf16 v[16:31], v[182:185], v[222:225], v[16:31]
	v_exp_f32_e32 v182, v88
	v_exp_f32_e32 v183, v89
	v_exp_f32_e32 v184, v90
	v_exp_f32_e32 v185, v92
	v_cmp_gt_f32_e32 vcc, 1.0, v177
	s_waitcnt vmcnt(0)
	s_barrier
	s_add_u32 m0, s86, 0x4000
	s_nop 0
	global_load_lds_dwordx4 v249, s[84:85]
	s_add_u32 m0, s86, 0x4380
	s_nop 0
	global_load_lds_dwordx4 v249, s[84:85] offset:128
	s_add_u32 s84, s84, 0x8000
	s_addc_u32 s85, s85, 0
	s_cbranch_vccz .LBB0_441
	s_and_saveexec_b64 s[2:3], s[6:7]
	ds_write_b32 v158, v177 offset:128
	s_or_b64 exec, exec, s[2:3]
	s_waitcnt lgkmcnt(0)
	v_add_u32_e32 v242, v131, v128
	ds_read_b128 v[226:229], v242 offset:224
	ds_read_b128 v[230:233], v242 offset:192
	ds_read_b128 v[234:237], v242 offset:160
	ds_read_b128 v[238:241], v242 offset:128
	s_waitcnt lgkmcnt(3)
	v_pk_mul_f32 v[12:13], v[12:13], v[226:227]
	s_waitcnt lgkmcnt(2)
	v_pk_mul_f32 v[8:9], v[8:9], v[230:231]
	s_waitcnt lgkmcnt(1)
	v_pk_mul_f32 v[4:5], v[4:5], v[234:235]
	v_pk_mul_f32 v[14:15], v[14:15], v[228:229]
	v_pk_mul_f32 v[10:11], v[10:11], v[232:233]
	v_pk_mul_f32 v[6:7], v[6:7], v[236:237]
	s_waitcnt lgkmcnt(0)
	v_pk_mul_f32 v[2:3], v[2:3], v[240:241]
	v_pk_mul_f32 v[0:1], v[0:1], v[238:239]
	v_pk_mul_f32 v[60:61], v[60:61], v[226:227]
	v_pk_mul_f32 v[56:57], v[56:57], v[230:231]
	v_pk_mul_f32 v[52:53], v[52:53], v[234:235]
	v_pk_mul_f32 v[62:63], v[62:63], v[228:229]
	v_pk_mul_f32 v[58:59], v[58:59], v[232:233]
	v_pk_mul_f32 v[54:55], v[54:55], v[236:237]
	v_pk_mul_f32 v[50:51], v[50:51], v[240:241]
	v_pk_mul_f32 v[48:49], v[48:49], v[238:239]
	v_pk_mul_f32 v[44:45], v[44:45], v[226:227]
	v_pk_mul_f32 v[40:41], v[40:41], v[230:231]
	v_pk_mul_f32 v[36:37], v[36:37], v[234:235]
	v_pk_mul_f32 v[46:47], v[46:47], v[228:229]
	v_pk_mul_f32 v[42:43], v[42:43], v[232:233]
	v_pk_mul_f32 v[38:39], v[38:39], v[236:237]
	v_pk_mul_f32 v[34:35], v[34:35], v[240:241]
	v_pk_mul_f32 v[32:33], v[32:33], v[238:239]
	v_pk_mul_f32 v[28:29], v[28:29], v[226:227]
	v_pk_mul_f32 v[24:25], v[24:25], v[230:231]
	v_pk_mul_f32 v[20:21], v[20:21], v[234:235]
	v_pk_mul_f32 v[30:31], v[30:31], v[228:229]
	v_pk_mul_f32 v[26:27], v[26:27], v[232:233]
	v_pk_mul_f32 v[22:23], v[22:23], v[236:237]
	v_pk_mul_f32 v[18:19], v[18:19], v[240:241]
	v_pk_mul_f32 v[16:17], v[16:17], v[238:239]
